# S5 pass-2 recurrence loop hand-scheduled (dual accumulators, batched LDS reads) on top of the attention-loop rewrites
# speedup vs baseline: 1.0758x; 1.0062x over previous
; template <int PASS>
; __device__ __forceinline__ void s5_task(CArgs* Ap, int l, int b, int g, int c, LAS unsigned char* wl, int lane) {
;     ...
;     if (PASS == 2) {
;         float pr = ab_re, pi = ab_im;
; #pragma unroll
;         for (int i = 0; i < 9; ++i) { const float t_ = pr * pr - pi * pi; pi = 2.f * pr * pi; pr = t_; }
;         const f32x2* S = SST + (size_t)((b * NGRP + g) * NCHUNK) * NST + p;
;         for (int cc = 0; cc < c; ++cc) { const f32x2 s = S[(size_t)cc * NST]; const float t_ = pr * xr - pi * xi + s.x; xi = pr * xi + pi * xr + s.y; xr = t_; }
.LBB0_876:
	global_load_dwordx2 v[188:189], v[58:59], off
	global_load_dwordx2 v[190:191], v[58:59], off offset:512
	global_load_dwordx2 v[192:193], v[58:59], off offset:1024
	global_load_dwordx2 v[194:195], v[58:59], off offset:1536
	global_load_dwordx2 v[196:197], v[58:59], off offset:2048
	global_load_dwordx2 v[198:199], v[58:59], off offset:2560
	global_load_dwordx2 v[200:201], v[58:59], off offset:3072
	global_load_dwordx2 v[202:203], v[58:59], off offset:3584
	s_mov_b64 s[34:35], 0x1000
	v_lshl_add_u64 v[58:59], v[58:59], 0, s[34:35]
	global_load_dwordx2 v[204:205], v[58:59], off
	global_load_dwordx2 v[206:207], v[58:59], off offset:512
	global_load_dwordx2 v[208:209], v[58:59], off offset:1024
	global_load_dwordx2 v[228:229], v[58:59], off offset:1536
	global_load_dwordx2 v[230:231], v[58:59], off offset:2048
	global_load_dwordx2 v[232:233], v[58:59], off offset:2560
	global_load_dwordx2 v[234:235], v[58:59], off offset:3072
	v_pk_mul_f32 v[62:63], v[56:57], v[50:51] op_sel:[0,1] op_sel_hi:[1,0]
	s_nop 0
	v_pk_fma_f32 v[64:65], v[54:55], v[50:51], v[62:63] neg_lo:[0,0,1] neg_hi:[0,0,1]
	v_pk_fma_f32 v[50:51], v[54:55], v[50:51], v[62:63]
	s_nop 0
	v_mov_b32_e32 v65, v51
	s_waitcnt vmcnt(14)
	v_pk_add_f32 v[50:51], v[64:65], v[188:189]
	s_cmp_le_u32 s1, 1
	s_cbranch_scc1 .Ls5pre_done
	v_pk_mul_f32 v[62:63], v[56:57], v[50:51] op_sel:[0,1] op_sel_hi:[1,0]
	s_nop 0
	v_pk_fma_f32 v[64:65], v[54:55], v[50:51], v[62:63] neg_lo:[0,0,1] neg_hi:[0,0,1]
	v_pk_fma_f32 v[50:51], v[54:55], v[50:51], v[62:63]
	s_nop 0
	v_mov_b32_e32 v65, v51
	s_waitcnt vmcnt(13)
	v_pk_add_f32 v[50:51], v[64:65], v[190:191]
	s_cmp_le_u32 s1, 2
	s_cbranch_scc1 .Ls5pre_done
	v_pk_mul_f32 v[62:63], v[56:57], v[50:51] op_sel:[0,1] op_sel_hi:[1,0]
	s_nop 0
	v_pk_fma_f32 v[64:65], v[54:55], v[50:51], v[62:63] neg_lo:[0,0,1] neg_hi:[0,0,1]
	v_pk_fma_f32 v[50:51], v[54:55], v[50:51], v[62:63]
	s_nop 0
	v_mov_b32_e32 v65, v51
	s_waitcnt vmcnt(12)
	v_pk_add_f32 v[50:51], v[64:65], v[192:193]
	s_cmp_le_u32 s1, 3
	s_cbranch_scc1 .Ls5pre_done
	v_pk_mul_f32 v[62:63], v[56:57], v[50:51] op_sel:[0,1] op_sel_hi:[1,0]
	s_nop 0
	v_pk_fma_f32 v[64:65], v[54:55], v[50:51], v[62:63] neg_lo:[0,0,1] neg_hi:[0,0,1]
	v_pk_fma_f32 v[50:51], v[54:55], v[50:51], v[62:63]
	s_nop 0
	v_mov_b32_e32 v65, v51
	s_waitcnt vmcnt(11)
	v_pk_add_f32 v[50:51], v[64:65], v[194:195]
	s_cmp_le_u32 s1, 4
	s_cbranch_scc1 .Ls5pre_done
	v_pk_mul_f32 v[62:63], v[56:57], v[50:51] op_sel:[0,1] op_sel_hi:[1,0]
	s_nop 0
	v_pk_fma_f32 v[64:65], v[54:55], v[50:51], v[62:63] neg_lo:[0,0,1] neg_hi:[0,0,1]
	v_pk_fma_f32 v[50:51], v[54:55], v[50:51], v[62:63]
	s_nop 0
	v_mov_b32_e32 v65, v51
	s_waitcnt vmcnt(10)
	v_pk_add_f32 v[50:51], v[64:65], v[196:197]
	s_cmp_le_u32 s1, 5
	s_cbranch_scc1 .Ls5pre_done
	v_pk_mul_f32 v[62:63], v[56:57], v[50:51] op_sel:[0,1] op_sel_hi:[1,0]
	s_nop 0
	v_pk_fma_f32 v[64:65], v[54:55], v[50:51], v[62:63] neg_lo:[0,0,1] neg_hi:[0,0,1]
	v_pk_fma_f32 v[50:51], v[54:55], v[50:51], v[62:63]
	s_nop 0
	v_mov_b32_e32 v65, v51
	s_waitcnt vmcnt(9)
	v_pk_add_f32 v[50:51], v[64:65], v[198:199]
	s_cmp_le_u32 s1, 6
	s_cbranch_scc1 .Ls5pre_done
	v_pk_mul_f32 v[62:63], v[56:57], v[50:51] op_sel:[0,1] op_sel_hi:[1,0]
	s_nop 0
	v_pk_fma_f32 v[64:65], v[54:55], v[50:51], v[62:63] neg_lo:[0,0,1] neg_hi:[0,0,1]
	v_pk_fma_f32 v[50:51], v[54:55], v[50:51], v[62:63]
	s_nop 0
	v_mov_b32_e32 v65, v51
	s_waitcnt vmcnt(8)
	v_pk_add_f32 v[50:51], v[64:65], v[200:201]
	s_cmp_le_u32 s1, 7
	s_cbranch_scc1 .Ls5pre_done
	v_pk_mul_f32 v[62:63], v[56:57], v[50:51] op_sel:[0,1] op_sel_hi:[1,0]
	s_nop 0
	v_pk_fma_f32 v[64:65], v[54:55], v[50:51], v[62:63] neg_lo:[0,0,1] neg_hi:[0,0,1]
	v_pk_fma_f32 v[50:51], v[54:55], v[50:51], v[62:63]
	s_nop 0
	v_mov_b32_e32 v65, v51
	s_waitcnt vmcnt(7)
	v_pk_add_f32 v[50:51], v[64:65], v[202:203]
	s_cmp_le_u32 s1, 8
	s_cbranch_scc1 .Ls5pre_done
	v_pk_mul_f32 v[62:63], v[56:57], v[50:51] op_sel:[0,1] op_sel_hi:[1,0]
	s_nop 0
	v_pk_fma_f32 v[64:65], v[54:55], v[50:51], v[62:63] neg_lo:[0,0,1] neg_hi:[0,0,1]
	v_pk_fma_f32 v[50:51], v[54:55], v[50:51], v[62:63]
	s_nop 0
	v_mov_b32_e32 v65, v51
	s_waitcnt vmcnt(6)
	v_pk_add_f32 v[50:51], v[64:65], v[204:205]
	s_cmp_le_u32 s1, 9
	s_cbranch_scc1 .Ls5pre_done
	v_pk_mul_f32 v[62:63], v[56:57], v[50:51] op_sel:[0,1] op_sel_hi:[1,0]
	s_nop 0
	v_pk_fma_f32 v[64:65], v[54:55], v[50:51], v[62:63] neg_lo:[0,0,1] neg_hi:[0,0,1]
	v_pk_fma_f32 v[50:51], v[54:55], v[50:51], v[62:63]
	s_nop 0
	v_mov_b32_e32 v65, v51
	s_waitcnt vmcnt(5)
	v_pk_add_f32 v[50:51], v[64:65], v[206:207]
	s_cmp_le_u32 s1, 10
	s_cbranch_scc1 .Ls5pre_done
	v_pk_mul_f32 v[62:63], v[56:57], v[50:51] op_sel:[0,1] op_sel_hi:[1,0]
	s_nop 0
	v_pk_fma_f32 v[64:65], v[54:55], v[50:51], v[62:63] neg_lo:[0,0,1] neg_hi:[0,0,1]
	v_pk_fma_f32 v[50:51], v[54:55], v[50:51], v[62:63]
	s_nop 0
	v_mov_b32_e32 v65, v51
	s_waitcnt vmcnt(4)
	v_pk_add_f32 v[50:51], v[64:65], v[208:209]
	s_cmp_le_u32 s1, 11
	s_cbranch_scc1 .Ls5pre_done
	v_pk_mul_f32 v[62:63], v[56:57], v[50:51] op_sel:[0,1] op_sel_hi:[1,0]
	s_nop 0
	v_pk_fma_f32 v[64:65], v[54:55], v[50:51], v[62:63] neg_lo:[0,0,1] neg_hi:[0,0,1]
	v_pk_fma_f32 v[50:51], v[54:55], v[50:51], v[62:63]
	s_nop 0
	v_mov_b32_e32 v65, v51
	s_waitcnt vmcnt(3)
	v_pk_add_f32 v[50:51], v[64:65], v[228:229]
	s_cmp_le_u32 s1, 12
	s_cbranch_scc1 .Ls5pre_done
	v_pk_mul_f32 v[62:63], v[56:57], v[50:51] op_sel:[0,1] op_sel_hi:[1,0]
	s_nop 0
	v_pk_fma_f32 v[64:65], v[54:55], v[50:51], v[62:63] neg_lo:[0,0,1] neg_hi:[0,0,1]
	v_pk_fma_f32 v[50:51], v[54:55], v[50:51], v[62:63]
	s_nop 0
	v_mov_b32_e32 v65, v51
	s_waitcnt vmcnt(2)
	v_pk_add_f32 v[50:51], v[64:65], v[230:231]
	s_cmp_le_u32 s1, 13
	s_cbranch_scc1 .Ls5pre_done
	v_pk_mul_f32 v[62:63], v[56:57], v[50:51] op_sel:[0,1] op_sel_hi:[1,0]
	s_nop 0
	v_pk_fma_f32 v[64:65], v[54:55], v[50:51], v[62:63] neg_lo:[0,0,1] neg_hi:[0,0,1]
	v_pk_fma_f32 v[50:51], v[54:55], v[50:51], v[62:63]
	s_nop 0
	v_mov_b32_e32 v65, v51
	s_waitcnt vmcnt(1)
	v_pk_add_f32 v[50:51], v[64:65], v[232:233]
	s_cmp_le_u32 s1, 14
	s_cbranch_scc1 .Ls5pre_done
	v_pk_mul_f32 v[62:63], v[56:57], v[50:51] op_sel:[0,1] op_sel_hi:[1,0]
	s_nop 0
	v_pk_fma_f32 v[64:65], v[54:55], v[50:51], v[62:63] neg_lo:[0,0,1] neg_hi:[0,0,1]
	v_pk_fma_f32 v[50:51], v[54:55], v[50:51], v[62:63]
	s_nop 0
	v_mov_b32_e32 v65, v51
	s_waitcnt vmcnt(0)
	v_pk_add_f32 v[50:51], v[64:65], v[234:235]
.Ls5pre_done:
	s_branch .LBB0_878
.LBB0_877:
	v_mov_b32_e32 v144, v145
	v_mov_b64_e32 v[50:51], v[144:145]

; #define LAS __attribute__((address_space(3)))
; __device__ __forceinline__ unsigned pk2(float lo, float hi) { return pg8::cvt_pk_bf16(lo, hi); }
; template <int PASS>
; __device__ __forceinline__ void s5_task(CArgs* Ap, int l, int b, int g, int c, LAS unsigned char* wl, int lane) {
;     ...
; #pragma unroll 4
;         for (int s = 0; s < 16; ++s) {
;             const f32x4 u0 = *(const LAS f32x4*)(us + s * 16), u1 = *(const LAS f32x4*)(us + s * 16 + 4), u2 = *(const LAS f32x4*)(us + s * 16 + 8), u3 = *(const LAS f32x4*)(us + s * 16 + 12);
;             f32x2 bu = (f32x2){0.f, 0.f};
; #pragma unroll
;             for (int i = 0; i < 4; ++i) bu = bb2[i] * (f32x2){u0[i], u0[i]} + bu;
; #pragma unroll
;             for (int i = 0; i < 4; ++i) bu = bb2[4 + i] * (f32x2){u1[i], u1[i]} + bu;
; #pragma unroll
;             for (int i = 0; i < 4; ++i) bu = bb2[8 + i] * (f32x2){u2[i], u2[i]} + bu;
; #pragma unroll
;             for (int i = 0; i < 4; ++i) bu = bb2[12 + i] * (f32x2){u3[i], u3[i]} + bu;
;             const float br_ = bu.x, bi_ = bu.y;
;             const float nxr = fmaf(ab_re, xr, fmaf(-ab_im, xi, br_)); const float nxi = fmaf(ab_re, xi, fmaf(ab_im, xr, bi_));
;             xr = nxr; xi = nxi;
;             if (PASS == 2) *(LAS unsigned*)(Xs + s * 136 + 2 * p) = pk2(xr, xi);
;         }
.LBB0_882:
	s_add_i32 s34, s25, s31
	v_mov_b32_e32 v83, s34
	ds_read_b128 v[228:231], v83
	ds_read_b128 v[232:235], v83 offset:16
	ds_read_b128 v[236:239], v83 offset:32
	ds_read_b128 v[240:243], v83 offset:48
	ds_read_b128 v[188:191], v83 offset:64
	ds_read_b128 v[192:195], v83 offset:80
	ds_read_b128 v[196:199], v83 offset:96
	ds_read_b128 v[200:203], v83 offset:112
	ds_read_b128 v[28:31], v83 offset:128
	ds_read_b128 v[98:101], v83 offset:144
	ds_read_b128 v[102:105], v83 offset:160
	ds_read_b128 v[106:109], v83 offset:176
	ds_read_b128 v[204:207], v83 offset:192
	ds_read_b128 v[244:247], v83 offset:208
	ds_read_b128 v[248:251], v83 offset:224
	ds_read_b128 v[160:163], v83 offset:240
	v_add_u32_e32 v17, s25, v16
	s_waitcnt lgkmcnt(12)
	v_pk_fma_f32 v[116:117], v[52:53], v[228:229], 0 op_sel_hi:[1,0,0]
	v_pk_fma_f32 v[126:127], v[54:55], v[228:229], 0 op_sel:[0,1,0] op_sel_hi:[1,1,0]
	v_pk_fma_f32 v[116:117], v[56:57], v[230:231], v[116:117] op_sel_hi:[1,0,1]
	v_pk_fma_f32 v[126:127], v[58:59], v[230:231], v[126:127] op_sel:[0,1,0]
	v_pk_fma_f32 v[116:117], v[60:61], v[232:233], v[116:117] op_sel_hi:[1,0,1]
	v_pk_fma_f32 v[126:127], v[20:21], v[232:233], v[126:127] op_sel:[0,1,0]
	v_pk_fma_f32 v[116:117], v[62:63], v[234:235], v[116:117] op_sel_hi:[1,0,1]
	v_pk_fma_f32 v[126:127], v[22:23], v[234:235], v[126:127] op_sel:[0,1,0]
	v_pk_fma_f32 v[116:117], v[66:67], v[236:237], v[116:117] op_sel_hi:[1,0,1]
	v_pk_fma_f32 v[126:127], v[68:69], v[236:237], v[126:127] op_sel:[0,1,0]
	v_pk_fma_f32 v[116:117], v[70:71], v[238:239], v[116:117] op_sel_hi:[1,0,1]
	v_pk_fma_f32 v[126:127], v[72:73], v[238:239], v[126:127] op_sel:[0,1,0]
	v_pk_fma_f32 v[116:117], v[74:75], v[240:241], v[116:117] op_sel_hi:[1,0,1]
	v_pk_fma_f32 v[126:127], v[76:77], v[240:241], v[126:127] op_sel:[0,1,0]
	v_pk_fma_f32 v[116:117], v[78:79], v[242:243], v[116:117] op_sel_hi:[1,0,1]
	v_pk_fma_f32 v[126:127], v[80:81], v[242:243], v[126:127] op_sel:[0,1,0]
	s_waitcnt lgkmcnt(8)
	v_pk_fma_f32 v[136:137], v[52:53], v[188:189], 0 op_sel_hi:[1,0,0]
	v_pk_add_f32 v[164:165], v[116:117], v[126:127]
	v_pk_fma_f32 v[150:151], v[54:55], v[188:189], 0 op_sel:[0,1,0] op_sel_hi:[1,1,0]
	v_pk_fma_f32 v[164:165], v[48:49], v[50:51], v[164:165] op_sel:[0,1,0] op_sel_hi:[1,0,1]
	v_pk_fma_f32 v[136:137], v[56:57], v[190:191], v[136:137] op_sel_hi:[1,0,1]
	v_pk_fma_f32 v[50:51], v[46:47], v[50:51], v[164:165]
	v_pk_fma_f32 v[150:151], v[58:59], v[190:191], v[150:151] op_sel:[0,1,0]
	v_cvt_pk_bf16_f32 v118, v50, v51
	v_pk_fma_f32 v[136:137], v[60:61], v[192:193], v[136:137] op_sel_hi:[1,0,1]
	ds_write_b32 v17, v118
	v_pk_fma_f32 v[150:151], v[20:21], v[192:193], v[150:151] op_sel:[0,1,0]
	v_pk_fma_f32 v[136:137], v[62:63], v[194:195], v[136:137] op_sel_hi:[1,0,1]
	v_pk_fma_f32 v[150:151], v[22:23], v[194:195], v[150:151] op_sel:[0,1,0]
	v_pk_fma_f32 v[136:137], v[66:67], v[196:197], v[136:137] op_sel_hi:[1,0,1]
	v_pk_fma_f32 v[150:151], v[68:69], v[196:197], v[150:151] op_sel:[0,1,0]
	v_pk_fma_f32 v[136:137], v[70:71], v[198:199], v[136:137] op_sel_hi:[1,0,1]
	v_pk_fma_f32 v[150:151], v[72:73], v[198:199], v[150:151] op_sel:[0,1,0]
	v_pk_fma_f32 v[136:137], v[74:75], v[200:201], v[136:137] op_sel_hi:[1,0,1]
	v_pk_fma_f32 v[150:151], v[76:77], v[200:201], v[150:151] op_sel:[0,1,0]
	v_pk_fma_f32 v[136:137], v[78:79], v[202:203], v[136:137] op_sel_hi:[1,0,1]
	v_pk_fma_f32 v[150:151], v[80:81], v[202:203], v[150:151] op_sel:[0,1,0]
	s_waitcnt lgkmcnt(5)
	v_pk_fma_f32 v[116:117], v[52:53], v[28:29], 0 op_sel_hi:[1,0,0]
	v_pk_add_f32 v[164:165], v[136:137], v[150:151]
	v_pk_fma_f32 v[126:127], v[54:55], v[28:29], 0 op_sel:[0,1,0] op_sel_hi:[1,1,0]
	v_pk_fma_f32 v[164:165], v[48:49], v[50:51], v[164:165] op_sel:[0,1,0] op_sel_hi:[1,0,1]
	v_pk_fma_f32 v[116:117], v[56:57], v[30:31], v[116:117] op_sel_hi:[1,0,1]
	v_pk_fma_f32 v[50:51], v[46:47], v[50:51], v[164:165]
	v_pk_fma_f32 v[126:127], v[58:59], v[30:31], v[126:127] op_sel:[0,1,0]
	v_cvt_pk_bf16_f32 v118, v50, v51
	v_pk_fma_f32 v[116:117], v[60:61], v[98:99], v[116:117] op_sel_hi:[1,0,1]
	ds_write_b32 v17, v118 offset:272
	v_pk_fma_f32 v[126:127], v[20:21], v[98:99], v[126:127] op_sel:[0,1,0]
	v_pk_fma_f32 v[116:117], v[62:63], v[100:101], v[116:117] op_sel_hi:[1,0,1]
	v_pk_fma_f32 v[126:127], v[22:23], v[100:101], v[126:127] op_sel:[0,1,0]
	v_pk_fma_f32 v[116:117], v[66:67], v[102:103], v[116:117] op_sel_hi:[1,0,1]
	v_pk_fma_f32 v[126:127], v[68:69], v[102:103], v[126:127] op_sel:[0,1,0]
	v_pk_fma_f32 v[116:117], v[70:71], v[104:105], v[116:117] op_sel_hi:[1,0,1]
	v_pk_fma_f32 v[126:127], v[72:73], v[104:105], v[126:127] op_sel:[0,1,0]
	v_pk_fma_f32 v[116:117], v[74:75], v[106:107], v[116:117] op_sel_hi:[1,0,1]
	v_pk_fma_f32 v[126:127], v[76:77], v[106:107], v[126:127] op_sel:[0,1,0]
	v_pk_fma_f32 v[116:117], v[78:79], v[108:109], v[116:117] op_sel_hi:[1,0,1]
	v_pk_fma_f32 v[126:127], v[80:81], v[108:109], v[126:127] op_sel:[0,1,0]
	s_waitcnt lgkmcnt(2)
	v_pk_fma_f32 v[136:137], v[52:53], v[204:205], 0 op_sel_hi:[1,0,0]
	v_pk_add_f32 v[164:165], v[116:117], v[126:127]
	v_pk_fma_f32 v[150:151], v[54:55], v[204:205], 0 op_sel:[0,1,0] op_sel_hi:[1,1,0]
	v_pk_fma_f32 v[164:165], v[48:49], v[50:51], v[164:165] op_sel:[0,1,0] op_sel_hi:[1,0,1]
	v_pk_fma_f32 v[136:137], v[56:57], v[206:207], v[136:137] op_sel_hi:[1,0,1]
	v_pk_fma_f32 v[50:51], v[46:47], v[50:51], v[164:165]
	v_pk_fma_f32 v[150:151], v[58:59], v[206:207], v[150:151] op_sel:[0,1,0]
	v_cvt_pk_bf16_f32 v118, v50, v51
	v_pk_fma_f32 v[136:137], v[60:61], v[244:245], v[136:137] op_sel_hi:[1,0,1]
	ds_write_b32 v17, v118 offset:544
	v_pk_fma_f32 v[150:151], v[20:21], v[244:245], v[150:151] op_sel:[0,1,0]
	v_pk_fma_f32 v[136:137], v[62:63], v[246:247], v[136:137] op_sel_hi:[1,0,1]
	v_pk_fma_f32 v[150:151], v[22:23], v[246:247], v[150:151] op_sel:[0,1,0]
	v_pk_fma_f32 v[136:137], v[66:67], v[248:249], v[136:137] op_sel_hi:[1,0,1]
	v_pk_fma_f32 v[150:151], v[68:69], v[248:249], v[150:151] op_sel:[0,1,0]
	v_pk_fma_f32 v[136:137], v[70:71], v[250:251], v[136:137] op_sel_hi:[1,0,1]
	v_pk_fma_f32 v[150:151], v[72:73], v[250:251], v[150:151] op_sel:[0,1,0]
	v_pk_fma_f32 v[136:137], v[74:75], v[160:161], v[136:137] op_sel_hi:[1,0,1]
	v_pk_fma_f32 v[150:151], v[76:77], v[160:161], v[150:151] op_sel:[0,1,0]
	v_pk_fma_f32 v[136:137], v[78:79], v[162:163], v[136:137] op_sel_hi:[1,0,1]
	v_pk_fma_f32 v[150:151], v[80:81], v[162:163], v[150:151] op_sel:[0,1,0]
	s_addk_i32 s31, 0x100
	v_pk_add_f32 v[164:165], v[136:137], v[150:151]
	v_add_u32_e32 v16, 0x440, v16
	v_pk_fma_f32 v[164:165], v[48:49], v[50:51], v[164:165] op_sel:[0,1,0] op_sel_hi:[1,0,1]
	s_nop 0
	v_pk_fma_f32 v[50:51], v[46:47], v[50:51], v[164:165]
	s_cmpk_eq_i32 s31, 0x400
	v_cvt_pk_bf16_f32 v118, v50, v51
	ds_write_b32 v17, v118 offset:816
	s_cbranch_scc0 .LBB0_882
; #define LAS __attribute__((address_space(3)))
; __device__ __forceinline__ bf16_t f2bf(float f) { return (bf16_t)(pk2(f, f) & 0xffffu); }
; __device__ __forceinline__ float gelu_tanh(float x) { const float z = 0.7978845608f * (x + 0.044715f * x * x * x); const float e = fexp(2.f * z); const float th = 1.f - 2.f * __builtin_amdgcn_rcpf(e + 1.f); return 0.5f * x * (1.f + th); }
; __device__ __forceinline__ void wave_lds_fence() { asm volatile("s_waitcnt lgkmcnt(0)" ::: "memory"); }
; template <int PASS>
; __device__ __forceinline__ void s5_task(CArgs* Ap, int l, int b, int g, int c, LAS unsigned char* wl, int lane) {
;     ...
;         if (PASS == 2) {
;             wave_lds_fence();
;             f32x4 y = (f32x4){0.f, 0.f, 0.f, 0.f};
; #pragma unroll
;             for (int kk = 0; kk < 4; ++kk) { const bf16x8 xa = *(const LAS bf16x8*)(Xs + n16 * 136 + 32 * kk + 8 * g4); y = __builtin_amdgcn_mfma_f32_16x16x32_bf16(xa, cB[kk], y, 0, 0, 0); }
; #pragma unroll
;             for (int i = 0; i < 4; ++i) { const int tl = 4 * g4 + i; const float uv = us[tl * 16 + n16]; const float v = gelu_tanh(y[i] + dval * uv);
;                 Y1[(row0 + tb + tl) * DSSM + g * 16 + n16] = f2bf(v); }
;         }
;         wave_lds_fence();
;     }
	s_waitcnt lgkmcnt(0)
	ds_read_b128 v[16:19], v93 offset:1024
	ds_read_b128 v[28:31], v93 offset:1088
	ds_read_b128 v[98:101], v93 offset:1152
	v_or_b32_e32 v144, s16, v35
	v_lshl_add_u64 v[82:83], s[0:1], 0, v[144:145]
	s_waitcnt lgkmcnt(2)
	v_mfma_f32_16x16x32_bf16 v[16:19], v[16:19], v[0:3], 0
	v_or_b32_e32 v144, s16, v90
	s_and_b64 vcc, exec, s[14:15]
	s_waitcnt lgkmcnt(1)
	v_mfma_f32_16x16x32_bf16 v[28:31], v[28:31], v[4:7], v[16:19]
	s_nop 3
	ds_read_b128 v[16:19], v93 offset:1216
	s_waitcnt lgkmcnt(1)
	v_mfma_f32_16x16x32_bf16 v[28:31], v[98:101], v[8:11], v[28:31]
	ds_read_b32 v98, v94
	ds_read_b32 v99, v95
	ds_read_b32 v100, v96
	ds_read_b32 v101, v97
	s_waitcnt lgkmcnt(4)
	v_mfma_f32_16x16x32_bf16 v[16:19], v[16:19], v[12:15], v[28:31]
	s_waitcnt vmcnt(0) lgkmcnt(3)
	s_nop 6
	v_fma_f32 v28, v45, v98, v16
	v_mul_f32_e32 v16, 0x3d372713, v28
	v_mul_f32_e32 v16, v28, v16
	v_fma_f32 v16, v28, v16, v28
	v_mul_f32_e32 v16, 0x3f4c422a, v16
	v_add_f32_e32 v16, v16, v16
	v_mul_f32_e32 v16, 0x3fb8aa3b, v16
	v_exp_f32_e32 v30, v16
	s_waitcnt lgkmcnt(2)
	v_fma_f32 v29, v45, v99, v17
	v_mul_f32_e32 v17, 0x3d372713, v29
	v_mul_f32_e32 v17, v29, v17
	v_add_f32_e32 v30, 1.0, v30
	v_rcp_f32_e32 v30, v30
	v_fma_f32 v17, v29, v17, v29
	v_mul_f32_e32 v17, 0x3f4c422a, v17
	v_add_f32_e32 v17, v17, v17
	v_fma_f32 v30, v30, -2.0, 1.0
	v_mul_f32_e32 v17, 0x3fb8aa3b, v17
	v_mul_f32_e32 v28, 0.5, v28
	v_add_f32_e32 v30, 1.0, v30
	v_exp_f32_e32 v31, v17
	v_lshlrev_b64 v[16:17], 11, v[82:83]
	v_mul_f32_e32 v28, v28, v30
	v_lshl_add_u64 v[16:17], v[24:25], 0, v[16:17]
	v_cvt_pk_bf16_f32 v28, v28, s0
	s_waitcnt lgkmcnt(1)
	v_fma_f32 v18, v45, v100, v18
	global_store_short v[16:17], v28, off
	v_mul_f32_e32 v16, 0x3d372713, v18
	v_mul_f32_e32 v16, v18, v16
	v_fma_f32 v16, v18, v16, v18
	v_mul_f32_e32 v16, 0x3f4c422a, v16
	v_add_f32_e32 v16, v16, v16
	v_mul_f32_e32 v16, 0x3fb8aa3b, v16
	v_add_f32_e32 v31, 1.0, v31
	v_exp_f32_e32 v28, v16
	v_rcp_f32_e32 v31, v31
	v_mul_f32_e32 v29, 0.5, v29
	v_lshl_add_u64 v[16:17], s[0:1], 0, v[144:145]
	v_add_f32_e32 v28, 1.0, v28
	v_fma_f32 v31, v31, -2.0, 1.0
	v_rcp_f32_e32 v28, v28
	v_add_f32_e32 v31, 1.0, v31
	v_mul_f32_e32 v29, v29, v31
	v_lshlrev_b64 v[16:17], 11, v[16:17]
	v_cvt_pk_bf16_f32 v29, v29, s0
	v_lshl_add_u64 v[16:17], v[24:25], 0, v[16:17]
	global_store_short v[16:17], v29, off
	v_fma_f32 v16, v28, -2.0, 1.0
	v_mul_f32_e32 v17, 0.5, v18
	v_add_f32_e32 v16, 1.0, v16
	s_waitcnt lgkmcnt(0)
	v_fmac_f32_e32 v19, v45, v101
	v_mul_f32_e32 v16, v17, v16
	v_mul_f32_e32 v17, 0x3d372713, v19
	v_mul_f32_e32 v17, v19, v17
	v_fma_f32 v17, v19, v17, v19
	v_mul_f32_e32 v17, 0x3f4c422a, v17
	v_add_f32_e32 v17, v17, v17
	v_mul_f32_e32 v17, 0x3fb8aa3b, v17
	v_exp_f32_e32 v18, v17
	v_or_b32_e32 v144, s16, v91
	v_cvt_pk_bf16_f32 v28, v16, s0
	v_lshl_add_u64 v[16:17], s[0:1], 0, v[144:145]
	v_add_f32_e32 v18, 1.0, v18
	v_rcp_f32_e32 v18, v18
	v_lshlrev_b64 v[16:17], 11, v[16:17]
	v_lshl_add_u64 v[16:17], v[24:25], 0, v[16:17]
	global_store_short v[16:17], v28, off
	v_fma_f32 v16, v18, -2.0, 1.0
	v_mul_f32_e32 v17, 0.5, v19
	v_add_f32_e32 v16, 1.0, v16
	v_mul_f32_e32 v16, v17, v16
	v_or_b32_e32 v144, s16, v92
	v_cvt_pk_bf16_f32 v18, v16, s0
	v_lshl_add_u64 v[16:17], s[0:1], 0, v[144:145]
	v_lshlrev_b64 v[16:17], 11, v[16:17]
	v_lshl_add_u64 v[16:17], v[24:25], 0, v[16:17]
	global_store_short v[16:17], v18, off
	s_waitcnt lgkmcnt(0)
	v_mov_b64_e32 v[16:17], v[26:27]
	s_mov_b32 s16, s17
	s_cbranch_vccz .LBB0_879
	s_add_i32 s30, s30, s89
	s_add_i32 s28, s28, s29
	s_cmpk_gt_i32 s30, 0xff
	s_cbranch_scc0 .LBB0_868

; __device__ __forceinline__ void nsa_wave(CArgs* Ap, int l, int b, int g, int tq0, const LAS float* lut, LAS float* imp, int lane) {
;     ...
;             if (__all(jm >= 0 && t - (jm * 64 + 32 * hh + 31) >= 1023)) softmax_half_far(acc, lutg, st, Od);
;             else { bf16x8 pB; softmax_half<1>(acc, (jm < 0 ? 0 : jm) * 64 + 32 * hh, jm >= 0, t, g4, lutg, st, Od, pB); }
;             const long p8 = p_to_fp8(acc);
; #pragma unroll
;             for (int q2 = 0; q2 < 4; ++q2) { const long pm = (qi == q2) ? p8 : 0l; pv_acch8(Od, vq[q2], pm); }
;             if (more) {
; #pragma unroll
;                 for (int q2 = 0; q2 < 4; ++q2) load_vh8(vq[q2], Vs8 + (size_t)jn[q2] * 4096, h1, lane); }
.LBB0_1275:
	v_sub_f32_e32 v24, v144, v213
	v_mul_f32_e32 v25, 0x43800000, v216
	v_mul_f32_e32 v26, 0x43800000, v217
	v_mul_f32_e32 v29, 0x43800000, v220
	v_mul_f32_e32 v30, 0x43800000, v221
	v_mov_b32_e32 v31, 0
	v_mov_b32_e32 v144, 0
	v_cvt_pk_fp8_f32 v144, v29, v30
	v_cvt_pk_fp8_f32 v31, v25, v26
	v_mul_f32_e32 v24, 0x3fb8aa3b, v24
	v_mul_f32_e32 v27, 0x43800000, v218
	v_mul_f32_e32 v28, 0x43800000, v219
	v_mul_f32_e32 v25, 0x43800000, v222
	v_mul_f32_e32 v26, 0x43800000, v223
	v_exp_f32_e32 v24, v24
	v_cvt_pk_fp8_f32 v144, v25, v26 op_sel:[0,0,1]
	v_cvt_pk_fp8_f32 v31, v27, v28 op_sel:[0,0,1]
	s_and_b64 vcc, exec, s[46:47]
	v_pk_mul_f32 v[22:23], v[22:23], v[24:25] op_sel_hi:[1,0]
	v_pk_mul_f32 v[20:21], v[20:21], v[24:25] op_sel_hi:[1,0]
	v_cndmask_b32_e64 v27, 0, v144, s[6:7]
	v_cndmask_b32_e64 v26, 0, v31, s[6:7]
	v_pk_mul_f32 v[18:19], v[18:19], v[24:25] op_sel_hi:[1,0]
	v_pk_mul_f32 v[16:17], v[16:17], v[24:25] op_sel_hi:[1,0]
	v_pk_mul_f32 v[14:15], v[14:15], v[24:25] op_sel_hi:[1,0]
	v_pk_mul_f32 v[12:13], v[12:13], v[24:25] op_sel_hi:[1,0]
	v_pk_mul_f32 v[10:11], v[10:11], v[24:25] op_sel_hi:[1,0]
	v_pk_mul_f32 v[8:9], v[8:9], v[24:25] op_sel_hi:[1,0]
	s_cbranch_vccnz .Lsel_pv_last
	s_waitcnt vmcnt(15)
	s_nop 0
	v_mfma_f32_16x16x32_fp8_fp8 v[20:23], v[40:41], v[26:27], v[20:23]
	v_mfma_f32_16x16x32_fp8_fp8 v[16:19], v[42:43], v[26:27], v[16:19]
	s_waitcnt vmcnt(14)
	v_mfma_f32_16x16x32_fp8_fp8 v[12:15], v[44:45], v[26:27], v[12:15]
	v_mfma_f32_16x16x32_fp8_fp8 v[8:11], v[46:47], v[26:27], v[8:11]
	v_cndmask_b32_e64 v27, 0, v144, s[8:9]
	v_cndmask_b32_e64 v26, 0, v31, s[8:9]
	s_waitcnt vmcnt(13)
	s_nop 0
	v_mfma_f32_16x16x32_fp8_fp8 v[20:23], v[56:57], v[26:27], v[20:23]
	v_mfma_f32_16x16x32_fp8_fp8 v[16:19], v[58:59], v[26:27], v[16:19]
	s_waitcnt vmcnt(12)
	v_mfma_f32_16x16x32_fp8_fp8 v[12:15], v[60:61], v[26:27], v[12:15]
	v_mfma_f32_16x16x32_fp8_fp8 v[8:11], v[62:63], v[26:27], v[8:11]
	v_cndmask_b32_e64 v27, 0, v144, s[10:11]
	v_cndmask_b32_e64 v26, 0, v31, s[10:11]
	s_waitcnt vmcnt(11)
	s_nop 0
	v_mfma_f32_16x16x32_fp8_fp8 v[20:23], v[74:75], v[26:27], v[20:23]
	v_mfma_f32_16x16x32_fp8_fp8 v[16:19], v[76:77], v[26:27], v[16:19]
	s_waitcnt vmcnt(10)
	v_mfma_f32_16x16x32_fp8_fp8 v[12:15], v[78:79], v[26:27], v[12:15]
	v_mfma_f32_16x16x32_fp8_fp8 v[8:11], v[80:81], v[26:27], v[8:11]
	v_cndmask_b32_e64 v27, 0, v144, s[12:13]
	v_cndmask_b32_e64 v26, 0, v31, s[12:13]
	s_waitcnt vmcnt(9)
	s_nop 0
	v_mfma_f32_16x16x32_fp8_fp8 v[20:23], v[106:107], v[26:27], v[20:23]
	v_mfma_f32_16x16x32_fp8_fp8 v[16:19], v[108:109], v[26:27], v[16:19]
	s_waitcnt vmcnt(8)
	v_mfma_f32_16x16x32_fp8_fp8 v[12:15], v[122:123], v[26:27], v[12:15]
	v_mfma_f32_16x16x32_fp8_fp8 v[8:11], v[124:125], v[26:27], v[8:11]
	v_lshl_or_b32 v144, s23, 11, v84
	s_add_u32 s48, s0, s66
	s_addc_u32 s49, s1, s67
	global_load_dwordx4 v[40:43], v144, s[48:49]
	global_load_dwordx4 v[44:47], v144, s[48:49] offset:1024
	s_add_u32 s48, s0, s64
	s_addc_u32 s49, s1, s65
	global_load_dwordx4 v[56:59], v144, s[48:49]
	global_load_dwordx4 v[60:63], v144, s[48:49] offset:1024
	s_add_u32 s48, s0, s76
	s_addc_u32 s49, s1, s77
	global_load_dwordx4 v[74:77], v144, s[48:49]
	global_load_dwordx4 v[78:81], v144, s[48:49] offset:1024
	s_add_u32 s48, s0, s68
	s_addc_u32 s49, s1, s69
	global_load_dwordx4 v[106:109], v144, s[48:49]
	global_load_dwordx4 v[122:125], v144, s[48:49] offset:1024
	s_branch .LBB0_1277
.Lsel_pv_last:
	s_waitcnt vmcnt(7)
	s_nop 0
	v_mfma_f32_16x16x32_fp8_fp8 v[20:23], v[40:41], v[26:27], v[20:23]
	v_mfma_f32_16x16x32_fp8_fp8 v[16:19], v[42:43], v[26:27], v[16:19]
	s_waitcnt vmcnt(6)
	v_mfma_f32_16x16x32_fp8_fp8 v[12:15], v[44:45], v[26:27], v[12:15]
	v_mfma_f32_16x16x32_fp8_fp8 v[8:11], v[46:47], v[26:27], v[8:11]
	v_cndmask_b32_e64 v27, 0, v144, s[8:9]
	v_cndmask_b32_e64 v26, 0, v31, s[8:9]
	s_waitcnt vmcnt(5)
	s_nop 0
	v_mfma_f32_16x16x32_fp8_fp8 v[20:23], v[56:57], v[26:27], v[20:23]
	v_mfma_f32_16x16x32_fp8_fp8 v[16:19], v[58:59], v[26:27], v[16:19]
	s_waitcnt vmcnt(4)
	v_mfma_f32_16x16x32_fp8_fp8 v[12:15], v[60:61], v[26:27], v[12:15]
	v_mfma_f32_16x16x32_fp8_fp8 v[8:11], v[62:63], v[26:27], v[8:11]
	v_cndmask_b32_e64 v27, 0, v144, s[10:11]
	v_cndmask_b32_e64 v26, 0, v31, s[10:11]
	s_waitcnt vmcnt(3)
	s_nop 0
	v_mfma_f32_16x16x32_fp8_fp8 v[20:23], v[74:75], v[26:27], v[20:23]
	v_mfma_f32_16x16x32_fp8_fp8 v[16:19], v[76:77], v[26:27], v[16:19]
	s_waitcnt vmcnt(2)
	v_mfma_f32_16x16x32_fp8_fp8 v[12:15], v[78:79], v[26:27], v[12:15]
	v_mfma_f32_16x16x32_fp8_fp8 v[8:11], v[80:81], v[26:27], v[8:11]
	v_cndmask_b32_e64 v27, 0, v144, s[12:13]
	v_cndmask_b32_e64 v26, 0, v31, s[12:13]
	s_waitcnt vmcnt(1)
	s_nop 0
	v_mfma_f32_16x16x32_fp8_fp8 v[20:23], v[106:107], v[26:27], v[20:23]
	v_mfma_f32_16x16x32_fp8_fp8 v[16:19], v[108:109], v[26:27], v[16:19]
	s_waitcnt vmcnt(0)
	v_mfma_f32_16x16x32_fp8_fp8 v[12:15], v[122:123], v[26:27], v[12:15]
	v_mfma_f32_16x16x32_fp8_fp8 v[8:11], v[124:125], v[26:27], v[8:11]
